# Z-instance epilogue: the eight per-row-block rinv values read from LDS once at the first block (no per-block LDS round trip and branches)
# baseline (speedup 1.0000x reference)
;     __device__ __forceinline__ void operator()(const f32x4 (&acc)[2][2][4][2], const Unit& u, int wr, int wc, int fr, int fq) const {
;     ...
;             for (int m = 0; m < 4; ++m) {
;                 const int row = row0 + ai * HALF + m * 16;
;                 float rs = 1.0f; if (ss) rs = R[wr * 64 + fr + ai * HALF + m * 16];
.LBB0_447:
	s_and_b64 vcc, exec, s[6:7]
	v_lshl_add_u32 v165, v162, 2, s19
	s_cbranch_vccnz .LBB0_449
	ds_read_b32 v160, v165
	ds_read_b32 v173, v165 offset:64
	ds_read_b32 v174, v165 offset:128
	ds_read_b32 v175, v165 offset:192
	ds_read_b32 v176, v165 offset:512
	ds_read_b32 v177, v165 offset:576
	ds_read_b32 v178, v165 offset:640
	ds_read_b32 v179, v165 offset:704
	s_branch .LBB0_450
.LBB0_449:
	v_mov_b32_e32 v160, 1.0
	v_mov_b32_e32 v173, 1.0
	v_mov_b32_e32 v174, 1.0
	v_mov_b32_e32 v175, 1.0
	v_mov_b32_e32 v176, 1.0
	v_mov_b32_e32 v177, 1.0
	v_mov_b32_e32 v178, 1.0
	v_mov_b32_e32 v179, 1.0

;     __device__ __forceinline__ void operator()(const f32x4 (&acc)[2][2][4][2], const Unit& u, int wr, int wc, int fr, int fq) const {
;     ...
;                 const int row = row0 + ai * HALF + m * 16;
;                 float rs = 1.0f; if (ss) rs = R[wr * 64 + fr + ai * HALF + m * 16];
;                 bf16_t* rowp = base + (size_t)row * ldc + col0; float sq = 0.f;
; #pragma unroll
;                 for (int bj = 0; bj < 2; ++bj) { f32x4 v0 = acc[ai][bj][m][0] * rs + bv[bj][0], v1 = acc[ai][bj][m][1] * rs + bv[bj][1];
;                     if (act) { const f32x2v a = gelu_tanh_pk((f32x2v){v0[0], v0[1]}), b = gelu_tanh_pk((f32x2v){v0[2], v0[3]}), c = gelu_tanh_pk((f32x2v){v1[0], v1[1]}), d = gelu_tanh_pk((f32x2v){v1[2], v1[3]});
;                         v0 = (f32x4){a.x, a.y, b.x, b.y}; v1 = (f32x4){c.x, c.y, d.x, d.y}; }
.LBB0_458:
	v_mov_b32_e32 v132, v173
	s_waitcnt lgkmcnt(0)
	v_pk_fma_f32 v[128:129], v[128:129], v[132:133], v[80:81] op_sel_hi:[1,0,1]
	v_pk_fma_f32 v[126:127], v[126:127], v[132:133], v[78:79] op_sel_hi:[1,0,1]
	v_pk_fma_f32 v[124:125], v[124:125], v[132:133], v[76:77] op_sel_hi:[1,0,1]
	s_and_b64 vcc, exec, s[10:11]
	v_pk_fma_f32 v[122:123], v[122:123], v[132:133], v[74:75] op_sel_hi:[1,0,1]
	s_cbranch_vccnz .LBB0_463
	v_pk_mul_f32 v[130:131], v[128:129], v[128:129]
	v_pk_mul_f32 v[134:135], v[126:127], v[126:127]
	v_pk_mul_f32 v[136:137], v[124:125], v[124:125]
	v_pk_mul_f32 v[142:143], v[122:123], v[122:123]
	v_pk_fma_f32 v[134:135], v[134:135], s[86:87], 1.0 op_sel_hi:[1,0,0]
	v_pk_fma_f32 v[130:131], v[130:131], s[86:87], 1.0 op_sel_hi:[1,0,0]
	v_pk_fma_f32 v[142:143], v[142:143], s[86:87], 1.0 op_sel_hi:[1,0,0]
	v_pk_fma_f32 v[136:137], v[136:137], s[86:87], 1.0 op_sel_hi:[1,0,0]
	v_pk_mul_f32 v[134:135], v[126:127], v[134:135]
	v_pk_mul_f32 v[130:131], v[128:129], v[130:131]
	v_pk_mul_f32 v[142:143], v[122:123], v[142:143]
	v_pk_mul_f32 v[136:137], v[124:125], v[136:137]
	v_pk_mul_f32 v[134:135], v[134:135], s[94:95] op_sel_hi:[1,0]
	v_pk_mul_f32 v[130:131], v[130:131], s[94:95] op_sel_hi:[1,0]
	v_pk_mul_f32 v[142:143], v[142:143], s[94:95] op_sel_hi:[1,0]
	v_pk_mul_f32 v[136:137], v[136:137], s[94:95] op_sel_hi:[1,0]
	v_exp_f32_e32 v134, v134
	v_exp_f32_e32 v135, v135
	v_exp_f32_e32 v130, v130
	v_exp_f32_e32 v131, v131
	v_exp_f32_e32 v142, v142
	v_exp_f32_e32 v143, v143
	v_exp_f32_e32 v136, v136
	v_exp_f32_e32 v137, v137
	v_pk_add_f32 v[134:135], v[134:135], 1.0 op_sel_hi:[1,0]
	v_pk_add_f32 v[130:131], v[130:131], 1.0 op_sel_hi:[1,0]
	v_pk_add_f32 v[142:143], v[142:143], 1.0 op_sel_hi:[1,0]
	v_pk_add_f32 v[136:137], v[136:137], 1.0 op_sel_hi:[1,0]
	v_rcp_f32_e32 v134, v134
	v_rcp_f32_e32 v135, v135
	v_rcp_f32_e32 v130, v130
	v_rcp_f32_e32 v131, v131
	v_rcp_f32_e32 v142, v142
	v_rcp_f32_e32 v143, v143
	v_rcp_f32_e32 v136, v136
	v_rcp_f32_e32 v137, v137
	v_pk_mul_f32 v[126:127], v[126:127], v[134:135]
	v_pk_mul_f32 v[128:129], v[128:129], v[130:131]
	v_pk_mul_f32 v[122:123], v[122:123], v[142:143]
	v_pk_mul_f32 v[124:125], v[124:125], v[136:137]

;     __device__ __forceinline__ void operator()(const f32x4 (&acc)[2][2][4][2], const Unit& u, int wr, int wc, int fr, int fq) const {
;     ...
;                 const int row = row0 + ai * HALF + m * 16;
;                 float rs = 1.0f; if (ss) rs = R[wr * 64 + fr + ai * HALF + m * 16];
;                 bf16_t* rowp = base + (size_t)row * ldc + col0; float sq = 0.f;
; #pragma unroll
;                 for (int bj = 0; bj < 2; ++bj) { f32x4 v0 = acc[ai][bj][m][0] * rs + bv[bj][0], v1 = acc[ai][bj][m][1] * rs + bv[bj][1];
;                     if (act) { const f32x2v a = gelu_tanh_pk((f32x2v){v0[0], v0[1]}), b = gelu_tanh_pk((f32x2v){v0[2], v0[3]}), c = gelu_tanh_pk((f32x2v){v1[0], v1[1]}), d = gelu_tanh_pk((f32x2v){v1[2], v1[3]});
;                         v0 = (f32x4){a.x, a.y, b.x, b.y}; v1 = (f32x4){c.x, c.y, d.x, d.y}; }
.LBB0_469:
	v_mov_b32_e32 v116, v174
	s_waitcnt lgkmcnt(0)
	v_pk_fma_f32 v[112:113], v[112:113], v[116:117], v[80:81] op_sel_hi:[1,0,1]
	v_pk_fma_f32 v[110:111], v[110:111], v[116:117], v[78:79] op_sel_hi:[1,0,1]
	v_pk_fma_f32 v[108:109], v[108:109], v[116:117], v[76:77] op_sel_hi:[1,0,1]
	s_and_b64 vcc, exec, s[10:11]
	v_pk_fma_f32 v[106:107], v[106:107], v[116:117], v[74:75] op_sel_hi:[1,0,1]
	s_cbranch_vccnz .LBB0_474
	v_pk_mul_f32 v[114:115], v[112:113], v[112:113]
	v_pk_mul_f32 v[118:119], v[110:111], v[110:111]
	v_pk_mul_f32 v[120:121], v[108:109], v[108:109]
	v_pk_mul_f32 v[122:123], v[106:107], v[106:107]
	v_pk_fma_f32 v[118:119], v[118:119], s[86:87], 1.0 op_sel_hi:[1,0,0]
	v_pk_fma_f32 v[114:115], v[114:115], s[86:87], 1.0 op_sel_hi:[1,0,0]
	v_pk_fma_f32 v[122:123], v[122:123], s[86:87], 1.0 op_sel_hi:[1,0,0]
	v_pk_fma_f32 v[120:121], v[120:121], s[86:87], 1.0 op_sel_hi:[1,0,0]
	v_pk_mul_f32 v[118:119], v[110:111], v[118:119]
	v_pk_mul_f32 v[114:115], v[112:113], v[114:115]
	v_pk_mul_f32 v[122:123], v[106:107], v[122:123]
	v_pk_mul_f32 v[120:121], v[108:109], v[120:121]
	v_pk_mul_f32 v[118:119], v[118:119], s[94:95] op_sel_hi:[1,0]
	v_pk_mul_f32 v[114:115], v[114:115], s[94:95] op_sel_hi:[1,0]
	v_pk_mul_f32 v[122:123], v[122:123], s[94:95] op_sel_hi:[1,0]
	v_pk_mul_f32 v[120:121], v[120:121], s[94:95] op_sel_hi:[1,0]
	v_exp_f32_e32 v118, v118
	v_exp_f32_e32 v119, v119
	v_exp_f32_e32 v114, v114
	v_exp_f32_e32 v115, v115
	v_exp_f32_e32 v122, v122
	v_exp_f32_e32 v123, v123
	v_exp_f32_e32 v120, v120
	v_exp_f32_e32 v121, v121
	v_pk_add_f32 v[118:119], v[118:119], 1.0 op_sel_hi:[1,0]
	v_pk_add_f32 v[114:115], v[114:115], 1.0 op_sel_hi:[1,0]
	v_pk_add_f32 v[122:123], v[122:123], 1.0 op_sel_hi:[1,0]
	v_pk_add_f32 v[120:121], v[120:121], 1.0 op_sel_hi:[1,0]
	v_rcp_f32_e32 v118, v118
	v_rcp_f32_e32 v119, v119
	v_rcp_f32_e32 v114, v114
	v_rcp_f32_e32 v115, v115
	v_rcp_f32_e32 v122, v122
	v_rcp_f32_e32 v123, v123
	v_rcp_f32_e32 v120, v120
	v_rcp_f32_e32 v121, v121
	v_pk_mul_f32 v[110:111], v[110:111], v[118:119]
	v_pk_mul_f32 v[112:113], v[112:113], v[114:115]
	v_pk_mul_f32 v[106:107], v[106:107], v[122:123]
	v_pk_mul_f32 v[108:109], v[108:109], v[120:121]

;     __device__ __forceinline__ void operator()(const f32x4 (&acc)[2][2][4][2], const Unit& u, int wr, int wc, int fr, int fq) const {
;     ...
;                 const int row = row0 + ai * HALF + m * 16;
;                 float rs = 1.0f; if (ss) rs = R[wr * 64 + fr + ai * HALF + m * 16];
;                 bf16_t* rowp = base + (size_t)row * ldc + col0; float sq = 0.f;
; #pragma unroll
;                 for (int bj = 0; bj < 2; ++bj) { f32x4 v0 = acc[ai][bj][m][0] * rs + bv[bj][0], v1 = acc[ai][bj][m][1] * rs + bv[bj][1];
;                     if (act) { const f32x2v a = gelu_tanh_pk((f32x2v){v0[0], v0[1]}), b = gelu_tanh_pk((f32x2v){v0[2], v0[3]}), c = gelu_tanh_pk((f32x2v){v1[0], v1[1]}), d = gelu_tanh_pk((f32x2v){v1[2], v1[3]});
;                         v0 = (f32x4){a.x, a.y, b.x, b.y}; v1 = (f32x4){c.x, c.y, d.x, d.y}; }
.LBB0_480:
	v_mov_b32_e32 v100, v175
	s_waitcnt lgkmcnt(0)
	v_pk_fma_f32 v[96:97], v[96:97], v[100:101], v[80:81] op_sel_hi:[1,0,1]
	v_pk_fma_f32 v[94:95], v[94:95], v[100:101], v[78:79] op_sel_hi:[1,0,1]
	v_pk_fma_f32 v[92:93], v[92:93], v[100:101], v[76:77] op_sel_hi:[1,0,1]
	s_and_b64 vcc, exec, s[10:11]
	v_pk_fma_f32 v[90:91], v[90:91], v[100:101], v[74:75] op_sel_hi:[1,0,1]
	s_cbranch_vccnz .LBB0_485
	v_pk_mul_f32 v[98:99], v[96:97], v[96:97]
	v_pk_mul_f32 v[102:103], v[94:95], v[94:95]
	v_pk_mul_f32 v[104:105], v[92:93], v[92:93]
	v_pk_mul_f32 v[106:107], v[90:91], v[90:91]
	v_pk_fma_f32 v[102:103], v[102:103], s[86:87], 1.0 op_sel_hi:[1,0,0]
	v_pk_fma_f32 v[98:99], v[98:99], s[86:87], 1.0 op_sel_hi:[1,0,0]
	v_pk_fma_f32 v[106:107], v[106:107], s[86:87], 1.0 op_sel_hi:[1,0,0]
	v_pk_fma_f32 v[104:105], v[104:105], s[86:87], 1.0 op_sel_hi:[1,0,0]
	v_pk_mul_f32 v[102:103], v[94:95], v[102:103]
	v_pk_mul_f32 v[98:99], v[96:97], v[98:99]
	v_pk_mul_f32 v[106:107], v[90:91], v[106:107]
	v_pk_mul_f32 v[104:105], v[92:93], v[104:105]
	v_pk_mul_f32 v[102:103], v[102:103], s[94:95] op_sel_hi:[1,0]
	v_pk_mul_f32 v[98:99], v[98:99], s[94:95] op_sel_hi:[1,0]
	v_pk_mul_f32 v[106:107], v[106:107], s[94:95] op_sel_hi:[1,0]
	v_pk_mul_f32 v[104:105], v[104:105], s[94:95] op_sel_hi:[1,0]
	v_exp_f32_e32 v102, v102
	v_exp_f32_e32 v103, v103
	v_exp_f32_e32 v98, v98
	v_exp_f32_e32 v99, v99
	v_exp_f32_e32 v106, v106
	v_exp_f32_e32 v107, v107
	v_exp_f32_e32 v104, v104
	v_exp_f32_e32 v105, v105
	v_pk_add_f32 v[102:103], v[102:103], 1.0 op_sel_hi:[1,0]
	v_pk_add_f32 v[98:99], v[98:99], 1.0 op_sel_hi:[1,0]
	v_pk_add_f32 v[106:107], v[106:107], 1.0 op_sel_hi:[1,0]
	v_pk_add_f32 v[104:105], v[104:105], 1.0 op_sel_hi:[1,0]
	v_rcp_f32_e32 v102, v102
	v_rcp_f32_e32 v103, v103
	v_rcp_f32_e32 v98, v98
	v_rcp_f32_e32 v99, v99
	v_rcp_f32_e32 v106, v106
	v_rcp_f32_e32 v107, v107
	v_rcp_f32_e32 v104, v104
	v_rcp_f32_e32 v105, v105
	v_pk_mul_f32 v[94:95], v[94:95], v[102:103]
	v_pk_mul_f32 v[96:97], v[96:97], v[98:99]
	v_pk_mul_f32 v[90:91], v[90:91], v[106:107]
	v_pk_mul_f32 v[92:93], v[92:93], v[104:105]

;     __device__ __forceinline__ void operator()(const f32x4 (&acc)[2][2][4][2], const Unit& u, int wr, int wc, int fr, int fq) const {
;     ...
;                 const int row = row0 + ai * HALF + m * 16;
;                 float rs = 1.0f; if (ss) rs = R[wr * 64 + fr + ai * HALF + m * 16];
;                 bf16_t* rowp = base + (size_t)row * ldc + col0; float sq = 0.f;
; #pragma unroll
;                 for (int bj = 0; bj < 2; ++bj) { f32x4 v0 = acc[ai][bj][m][0] * rs + bv[bj][0], v1 = acc[ai][bj][m][1] * rs + bv[bj][1];
;                     if (act) { const f32x2v a = gelu_tanh_pk((f32x2v){v0[0], v0[1]}), b = gelu_tanh_pk((f32x2v){v0[2], v0[3]}), c = gelu_tanh_pk((f32x2v){v1[0], v1[1]}), d = gelu_tanh_pk((f32x2v){v1[2], v1[3]});
;                         v0 = (f32x4){a.x, a.y, b.x, b.y}; v1 = (f32x4){c.x, c.y, d.x, d.y}; }
.LBB0_491:
	v_mov_b32_e32 v84, v176
	s_waitcnt lgkmcnt(0)
	v_pk_fma_f32 v[64:65], v[64:65], v[84:85], v[80:81] op_sel_hi:[1,0,1]
	v_pk_fma_f32 v[62:63], v[62:63], v[84:85], v[78:79] op_sel_hi:[1,0,1]
	v_pk_fma_f32 v[60:61], v[60:61], v[84:85], v[76:77] op_sel_hi:[1,0,1]
	s_and_b64 vcc, exec, s[10:11]
	v_pk_fma_f32 v[58:59], v[58:59], v[84:85], v[74:75] op_sel_hi:[1,0,1]
	s_cbranch_vccnz .LBB0_496
	v_pk_mul_f32 v[82:83], v[64:65], v[64:65]
	v_pk_mul_f32 v[86:87], v[62:63], v[62:63]
	v_pk_mul_f32 v[88:89], v[60:61], v[60:61]
	v_pk_mul_f32 v[90:91], v[58:59], v[58:59]
	v_pk_fma_f32 v[86:87], v[86:87], s[86:87], 1.0 op_sel_hi:[1,0,0]
	v_pk_fma_f32 v[82:83], v[82:83], s[86:87], 1.0 op_sel_hi:[1,0,0]
	v_pk_fma_f32 v[90:91], v[90:91], s[86:87], 1.0 op_sel_hi:[1,0,0]
	v_pk_fma_f32 v[88:89], v[88:89], s[86:87], 1.0 op_sel_hi:[1,0,0]
	v_pk_mul_f32 v[86:87], v[62:63], v[86:87]
	v_pk_mul_f32 v[82:83], v[64:65], v[82:83]
	v_pk_mul_f32 v[90:91], v[58:59], v[90:91]
	v_pk_mul_f32 v[88:89], v[60:61], v[88:89]
	v_pk_mul_f32 v[86:87], v[86:87], s[94:95] op_sel_hi:[1,0]
	v_pk_mul_f32 v[82:83], v[82:83], s[94:95] op_sel_hi:[1,0]
	v_pk_mul_f32 v[90:91], v[90:91], s[94:95] op_sel_hi:[1,0]
	v_pk_mul_f32 v[88:89], v[88:89], s[94:95] op_sel_hi:[1,0]
	v_exp_f32_e32 v86, v86
	v_exp_f32_e32 v87, v87
	v_exp_f32_e32 v82, v82
	v_exp_f32_e32 v83, v83
	v_exp_f32_e32 v90, v90
	v_exp_f32_e32 v91, v91
	v_exp_f32_e32 v88, v88
	v_exp_f32_e32 v89, v89
	v_pk_add_f32 v[86:87], v[86:87], 1.0 op_sel_hi:[1,0]
	v_pk_add_f32 v[82:83], v[82:83], 1.0 op_sel_hi:[1,0]
	v_pk_add_f32 v[90:91], v[90:91], 1.0 op_sel_hi:[1,0]
	v_pk_add_f32 v[88:89], v[88:89], 1.0 op_sel_hi:[1,0]
	v_rcp_f32_e32 v86, v86
	v_rcp_f32_e32 v87, v87
	v_rcp_f32_e32 v82, v82
	v_rcp_f32_e32 v83, v83
	v_rcp_f32_e32 v90, v90
	v_rcp_f32_e32 v91, v91
	v_rcp_f32_e32 v88, v88
	v_rcp_f32_e32 v89, v89
	v_pk_mul_f32 v[62:63], v[62:63], v[86:87]
	v_pk_mul_f32 v[64:65], v[64:65], v[82:83]
	v_pk_mul_f32 v[58:59], v[58:59], v[90:91]
	v_pk_mul_f32 v[60:61], v[60:61], v[88:89]

;     __device__ __forceinline__ void operator()(const f32x4 (&acc)[2][2][4][2], const Unit& u, int wr, int wc, int fr, int fq) const {
;     ...
;                 const int row = row0 + ai * HALF + m * 16;
;                 float rs = 1.0f; if (ss) rs = R[wr * 64 + fr + ai * HALF + m * 16];
;                 bf16_t* rowp = base + (size_t)row * ldc + col0; float sq = 0.f;
; #pragma unroll
;                 for (int bj = 0; bj < 2; ++bj) { f32x4 v0 = acc[ai][bj][m][0] * rs + bv[bj][0], v1 = acc[ai][bj][m][1] * rs + bv[bj][1];
;                     if (act) { const f32x2v a = gelu_tanh_pk((f32x2v){v0[0], v0[1]}), b = gelu_tanh_pk((f32x2v){v0[2], v0[3]}), c = gelu_tanh_pk((f32x2v){v1[0], v1[1]}), d = gelu_tanh_pk((f32x2v){v1[2], v1[3]});
;                         v0 = (f32x4){a.x, a.y, b.x, b.y}; v1 = (f32x4){c.x, c.y, d.x, d.y}; }
.LBB0_502:
	v_mov_b32_e32 v52, v177
	s_waitcnt lgkmcnt(0)
	v_pk_fma_f32 v[48:49], v[48:49], v[52:53], v[80:81] op_sel_hi:[1,0,1]
	v_pk_fma_f32 v[46:47], v[46:47], v[52:53], v[78:79] op_sel_hi:[1,0,1]
	v_pk_fma_f32 v[44:45], v[44:45], v[52:53], v[76:77] op_sel_hi:[1,0,1]
	s_and_b64 vcc, exec, s[10:11]
	v_pk_fma_f32 v[42:43], v[42:43], v[52:53], v[74:75] op_sel_hi:[1,0,1]
	s_cbranch_vccnz .LBB0_507
	v_pk_mul_f32 v[50:51], v[48:49], v[48:49]
	v_pk_mul_f32 v[54:55], v[46:47], v[46:47]
	v_pk_mul_f32 v[56:57], v[44:45], v[44:45]
	v_pk_mul_f32 v[58:59], v[42:43], v[42:43]
	v_pk_fma_f32 v[54:55], v[54:55], s[86:87], 1.0 op_sel_hi:[1,0,0]
	v_pk_fma_f32 v[50:51], v[50:51], s[86:87], 1.0 op_sel_hi:[1,0,0]
	v_pk_fma_f32 v[58:59], v[58:59], s[86:87], 1.0 op_sel_hi:[1,0,0]
	v_pk_fma_f32 v[56:57], v[56:57], s[86:87], 1.0 op_sel_hi:[1,0,0]
	v_pk_mul_f32 v[54:55], v[46:47], v[54:55]
	v_pk_mul_f32 v[50:51], v[48:49], v[50:51]
	v_pk_mul_f32 v[58:59], v[42:43], v[58:59]
	v_pk_mul_f32 v[56:57], v[44:45], v[56:57]
	v_pk_mul_f32 v[54:55], v[54:55], s[94:95] op_sel_hi:[1,0]
	v_pk_mul_f32 v[50:51], v[50:51], s[94:95] op_sel_hi:[1,0]
	v_pk_mul_f32 v[58:59], v[58:59], s[94:95] op_sel_hi:[1,0]
	v_pk_mul_f32 v[56:57], v[56:57], s[94:95] op_sel_hi:[1,0]
	v_exp_f32_e32 v54, v54
	v_exp_f32_e32 v55, v55
	v_exp_f32_e32 v50, v50
	v_exp_f32_e32 v51, v51
	v_exp_f32_e32 v58, v58
	v_exp_f32_e32 v59, v59
	v_exp_f32_e32 v56, v56
	v_exp_f32_e32 v57, v57
	v_pk_add_f32 v[54:55], v[54:55], 1.0 op_sel_hi:[1,0]
	v_pk_add_f32 v[50:51], v[50:51], 1.0 op_sel_hi:[1,0]
	v_pk_add_f32 v[58:59], v[58:59], 1.0 op_sel_hi:[1,0]
	v_pk_add_f32 v[56:57], v[56:57], 1.0 op_sel_hi:[1,0]
	v_rcp_f32_e32 v54, v54
	v_rcp_f32_e32 v55, v55
	v_rcp_f32_e32 v50, v50
	v_rcp_f32_e32 v51, v51
	v_rcp_f32_e32 v58, v58
	v_rcp_f32_e32 v59, v59
	v_rcp_f32_e32 v56, v56
	v_rcp_f32_e32 v57, v57
	v_pk_mul_f32 v[46:47], v[46:47], v[54:55]
	v_pk_mul_f32 v[48:49], v[48:49], v[50:51]
	v_pk_mul_f32 v[42:43], v[42:43], v[58:59]
	v_pk_mul_f32 v[44:45], v[44:45], v[56:57]

;     __device__ __forceinline__ void operator()(const f32x4 (&acc)[2][2][4][2], const Unit& u, int wr, int wc, int fr, int fq) const {
;     ...
;                 const int row = row0 + ai * HALF + m * 16;
;                 float rs = 1.0f; if (ss) rs = R[wr * 64 + fr + ai * HALF + m * 16];
;                 bf16_t* rowp = base + (size_t)row * ldc + col0; float sq = 0.f;
; #pragma unroll
;                 for (int bj = 0; bj < 2; ++bj) { f32x4 v0 = acc[ai][bj][m][0] * rs + bv[bj][0], v1 = acc[ai][bj][m][1] * rs + bv[bj][1];
;                     if (act) { const f32x2v a = gelu_tanh_pk((f32x2v){v0[0], v0[1]}), b = gelu_tanh_pk((f32x2v){v0[2], v0[3]}), c = gelu_tanh_pk((f32x2v){v1[0], v1[1]}), d = gelu_tanh_pk((f32x2v){v1[2], v1[3]});
;                         v0 = (f32x4){a.x, a.y, b.x, b.y}; v1 = (f32x4){c.x, c.y, d.x, d.y}; }
.LBB0_513:
	v_mov_b32_e32 v36, v178
	s_waitcnt lgkmcnt(0)
	v_pk_fma_f32 v[32:33], v[32:33], v[36:37], v[80:81] op_sel_hi:[1,0,1]
	v_pk_fma_f32 v[30:31], v[30:31], v[36:37], v[78:79] op_sel_hi:[1,0,1]
	v_pk_fma_f32 v[28:29], v[28:29], v[36:37], v[76:77] op_sel_hi:[1,0,1]
	s_and_b64 vcc, exec, s[10:11]
	v_pk_fma_f32 v[26:27], v[26:27], v[36:37], v[74:75] op_sel_hi:[1,0,1]
	s_cbranch_vccnz .LBB0_518
	v_pk_mul_f32 v[34:35], v[32:33], v[32:33]
	v_pk_mul_f32 v[38:39], v[30:31], v[30:31]
	v_pk_mul_f32 v[40:41], v[28:29], v[28:29]
	v_pk_mul_f32 v[42:43], v[26:27], v[26:27]
	v_pk_fma_f32 v[38:39], v[38:39], s[86:87], 1.0 op_sel_hi:[1,0,0]
	v_pk_fma_f32 v[34:35], v[34:35], s[86:87], 1.0 op_sel_hi:[1,0,0]
	v_pk_fma_f32 v[42:43], v[42:43], s[86:87], 1.0 op_sel_hi:[1,0,0]
	v_pk_fma_f32 v[40:41], v[40:41], s[86:87], 1.0 op_sel_hi:[1,0,0]
	v_pk_mul_f32 v[38:39], v[30:31], v[38:39]
	v_pk_mul_f32 v[34:35], v[32:33], v[34:35]
	v_pk_mul_f32 v[42:43], v[26:27], v[42:43]
	v_pk_mul_f32 v[40:41], v[28:29], v[40:41]
	v_pk_mul_f32 v[38:39], v[38:39], s[94:95] op_sel_hi:[1,0]
	v_pk_mul_f32 v[34:35], v[34:35], s[94:95] op_sel_hi:[1,0]
	v_pk_mul_f32 v[42:43], v[42:43], s[94:95] op_sel_hi:[1,0]
	v_pk_mul_f32 v[40:41], v[40:41], s[94:95] op_sel_hi:[1,0]
	v_exp_f32_e32 v38, v38
	v_exp_f32_e32 v39, v39
	v_exp_f32_e32 v34, v34
	v_exp_f32_e32 v35, v35
	v_exp_f32_e32 v42, v42
	v_exp_f32_e32 v43, v43
	v_exp_f32_e32 v40, v40
	v_exp_f32_e32 v41, v41
	v_pk_add_f32 v[38:39], v[38:39], 1.0 op_sel_hi:[1,0]
	v_pk_add_f32 v[34:35], v[34:35], 1.0 op_sel_hi:[1,0]
	v_pk_add_f32 v[42:43], v[42:43], 1.0 op_sel_hi:[1,0]
	v_pk_add_f32 v[40:41], v[40:41], 1.0 op_sel_hi:[1,0]
	v_rcp_f32_e32 v38, v38
	v_rcp_f32_e32 v39, v39
	v_rcp_f32_e32 v34, v34
	v_rcp_f32_e32 v35, v35
	v_rcp_f32_e32 v42, v42
	v_rcp_f32_e32 v43, v43
	v_rcp_f32_e32 v40, v40
	v_rcp_f32_e32 v41, v41
	v_pk_mul_f32 v[30:31], v[30:31], v[38:39]
	v_pk_mul_f32 v[32:33], v[32:33], v[34:35]
	v_pk_mul_f32 v[26:27], v[26:27], v[42:43]
	v_pk_mul_f32 v[28:29], v[28:29], v[40:41]

;     __device__ __forceinline__ void operator()(const f32x4 (&acc)[2][2][4][2], const Unit& u, int wr, int wc, int fr, int fq) const {
;     ...
;                 const int row = row0 + ai * HALF + m * 16;
;                 float rs = 1.0f; if (ss) rs = R[wr * 64 + fr + ai * HALF + m * 16];
;                 bf16_t* rowp = base + (size_t)row * ldc + col0; float sq = 0.f;
; #pragma unroll
;                 for (int bj = 0; bj < 2; ++bj) { f32x4 v0 = acc[ai][bj][m][0] * rs + bv[bj][0], v1 = acc[ai][bj][m][1] * rs + bv[bj][1];
;                     if (act) { const f32x2v a = gelu_tanh_pk((f32x2v){v0[0], v0[1]}), b = gelu_tanh_pk((f32x2v){v0[2], v0[3]}), c = gelu_tanh_pk((f32x2v){v1[0], v1[1]}), d = gelu_tanh_pk((f32x2v){v1[2], v1[3]});
;                         v0 = (f32x4){a.x, a.y, b.x, b.y}; v1 = (f32x4){c.x, c.y, d.x, d.y}; }
.LBB0_524:
	s_movk_i32 s2, 0x2000
	v_mov_b32_e32 v20, v179
	s_waitcnt lgkmcnt(0)
	v_pk_fma_f32 v[16:17], v[16:17], v[20:21], v[80:81] op_sel_hi:[1,0,1]
	v_pk_fma_f32 v[14:15], v[14:15], v[20:21], v[78:79] op_sel_hi:[1,0,1]
	v_pk_fma_f32 v[12:13], v[12:13], v[20:21], v[76:77] op_sel_hi:[1,0,1]
	s_and_b64 vcc, exec, s[10:11]
	v_pk_fma_f32 v[10:11], v[10:11], v[20:21], v[74:75] op_sel_hi:[1,0,1]
	s_cbranch_vccnz .LBB0_529
	v_pk_mul_f32 v[18:19], v[16:17], v[16:17]
	v_pk_mul_f32 v[22:23], v[14:15], v[14:15]
	v_pk_mul_f32 v[24:25], v[12:13], v[12:13]
	v_pk_mul_f32 v[26:27], v[10:11], v[10:11]
	v_pk_fma_f32 v[22:23], v[22:23], s[86:87], 1.0 op_sel_hi:[1,0,0]
	v_pk_fma_f32 v[18:19], v[18:19], s[86:87], 1.0 op_sel_hi:[1,0,0]
	v_pk_fma_f32 v[26:27], v[26:27], s[86:87], 1.0 op_sel_hi:[1,0,0]
	v_pk_fma_f32 v[24:25], v[24:25], s[86:87], 1.0 op_sel_hi:[1,0,0]
	v_pk_mul_f32 v[22:23], v[14:15], v[22:23]
	v_pk_mul_f32 v[18:19], v[16:17], v[18:19]
	v_pk_mul_f32 v[26:27], v[10:11], v[26:27]
	v_pk_mul_f32 v[24:25], v[12:13], v[24:25]
	v_pk_mul_f32 v[22:23], v[22:23], s[94:95] op_sel_hi:[1,0]
	v_pk_mul_f32 v[18:19], v[18:19], s[94:95] op_sel_hi:[1,0]
	v_pk_mul_f32 v[26:27], v[26:27], s[94:95] op_sel_hi:[1,0]
	v_pk_mul_f32 v[24:25], v[24:25], s[94:95] op_sel_hi:[1,0]
	v_exp_f32_e32 v22, v22
	v_exp_f32_e32 v23, v23
	v_exp_f32_e32 v18, v18
	v_exp_f32_e32 v19, v19
	v_exp_f32_e32 v26, v26
	v_exp_f32_e32 v27, v27
	v_exp_f32_e32 v24, v24
	v_exp_f32_e32 v25, v25
	v_pk_add_f32 v[22:23], v[22:23], 1.0 op_sel_hi:[1,0]
	v_pk_add_f32 v[18:19], v[18:19], 1.0 op_sel_hi:[1,0]
	v_pk_add_f32 v[26:27], v[26:27], 1.0 op_sel_hi:[1,0]
	v_pk_add_f32 v[24:25], v[24:25], 1.0 op_sel_hi:[1,0]
	v_rcp_f32_e32 v22, v22
	v_rcp_f32_e32 v23, v23
	v_rcp_f32_e32 v18, v18
	v_rcp_f32_e32 v19, v19
	v_rcp_f32_e32 v26, v26
	v_rcp_f32_e32 v27, v27
	v_rcp_f32_e32 v24, v24
	v_rcp_f32_e32 v25, v25
	v_pk_mul_f32 v[14:15], v[14:15], v[22:23]
	v_pk_mul_f32 v[16:17], v[16:17], v[18:19]
	v_pk_mul_f32 v[10:11], v[10:11], v[26:27]
	v_pk_mul_f32 v[12:13], v[12:13], v[24:25]
